# P11 kind-2 (stream-K head) residual epilogue also batched/pipelined
# speedup vs baseline: 1.0063x; 1.0025x over previous
;     __device__ __forceinline__ void add_partial(f32x4 (&acc)[2][2][4][2], const Unit& u, int tid, int wid) const {
;     ...
;         asm volatile("" ::: "memory"); __builtin_amdgcn_s_barrier(); asm volatile("" ::: "memory");
;         const float* sp = slots + (size_t)u.slot * 65536;
; #pragma unroll
;         for (int a = 0; a < 2; ++a)
; #pragma unroll
;             for (int b = 0; b < 2; ++b)
; #pragma unroll
;                 for (int m = 0; m < 4; ++m)
;                 {
; #pragma unroll
;                   for (int n = 0; n < 2; ++n) acc[a][b][m][n] += *(const f32x4*)(sp + ((size_t)((((a * 2 + b) * 4 + m) * 2 + n) * 512 + tid)) * 4);
;                   if (m == 3) asm volatile("" : "+v"(acc[a][b][0][0]), "+v"(acc[a][b][0][1]), "+v"(acc[a][b][1][0]), "+v"(acc[a][b][1][1]), "+v"(acc[a][b][2][0]), "+v"(acc[a][b][2][1]), "+v"(acc[a][b][3][0]), "+v"(acc[a][b][3][1]) :: "memory"); }
.LBB0_1094:
	s_ashr_i32 s19, s18, 31
	s_lshl_b64 s[2:3], s[18:19], 18
	s_add_u32 s2, s45, s2
	s_barrier
	s_addc_u32 s3, s62, s3
	v_mov_b32_e32 v165, 0
	v_lshl_add_u64 v[6:7], s[2:3], 0, v[164:165]
	global_load_dwordx4 v[2:5], v164, s[2:3]
	s_movk_i32 s2, 0x2000
	v_add_co_u32_e32 v8, vcc, s2, v6
	s_movk_i32 s3, 0x4000
	s_nop 0
	v_addc_co_u32_e32 v9, vcc, 0, v7, vcc
	v_add_co_u32_e32 v12, vcc, s3, v6
	s_movk_i32 s3, 0x6000
	s_nop 0
	v_addc_co_u32_e32 v13, vcc, 0, v7, vcc
	v_add_co_u32_e32 v16, vcc, s3, v6
	s_mov_b32 s3, 0x8000
	s_nop 0
	v_addc_co_u32_e32 v17, vcc, 0, v7, vcc
	v_add_co_u32_e32 v20, vcc, s3, v6
	s_mov_b32 s3, 0xa000
	s_nop 0
	v_addc_co_u32_e32 v21, vcc, 0, v7, vcc
	v_add_co_u32_e32 v24, vcc, s3, v6
	global_load_dwordx4 v[8:11], v[8:9], off
	s_nop 0
	global_load_dwordx4 v[12:15], v[12:13], off
	s_nop 0
	global_load_dwordx4 v[16:19], v[16:17], off
	s_nop 0
	global_load_dwordx4 v[20:23], v[20:21], off
	v_addc_co_u32_e32 v25, vcc, 0, v7, vcc
	s_mov_b32 s3, 0xc000
	v_add_co_u32_e32 v28, vcc, s3, v6
	s_mov_b32 s3, 0xe000
	s_nop 0
	v_addc_co_u32_e32 v29, vcc, 0, v7, vcc
	v_add_co_u32_e32 v32, vcc, s3, v6
	global_load_dwordx4 v[24:27], v[24:25], off
	s_nop 0
	global_load_dwordx4 v[28:31], v[28:29], off
	v_addc_co_u32_e32 v33, vcc, 0, v7, vcc
	global_load_dwordx4 v[166:169], v[32:33], off
	s_mov_b32 s3, 0x10000
	v_add_co_u32_e32 v32, vcc, s3, v6
	s_mov_b32 s4, 0x12000
	s_nop 0
	v_addc_co_u32_e32 v33, vcc, 0, v7, vcc
	v_add_co_u32_e32 v170, vcc, s4, v6
	s_mov_b32 s5, 0x14000
	s_nop 0
	v_addc_co_u32_e32 v171, vcc, 0, v7, vcc
	v_add_co_u32_e32 v172, vcc, s5, v6
	s_mov_b32 s6, 0x16000
	s_nop 0
	v_addc_co_u32_e32 v173, vcc, 0, v7, vcc
	s_mov_b32 s3, 0x18000
	s_mov_b32 s4, 0x22000
	s_mov_b32 s5, 0x24000
	s_mov_b32 s7, 0x28000
	s_mov_b32 s8, 0x2a000
	s_mov_b32 s9, 0x2c000
	s_mov_b32 s10, 0x2e000
	s_lshl_b32 s1, s1, 8
	s_add_i32 s1, s1, s34
	s_waitcnt vmcnt(0)
	v_pk_add_f32 v[158:159], v[2:3], v[158:159]
	v_pk_add_f32 v[160:161], v[4:5], v[160:161]
	v_pk_add_f32 v[156:157], v[10:11], v[156:157]
	v_pk_add_f32 v[146:147], v[16:17], v[146:147]
	v_add_co_u32_e32 v16, vcc, s6, v6
	v_pk_add_f32 v[142:143], v[20:21], v[142:143]
	s_nop 0
	v_addc_co_u32_e32 v17, vcc, 0, v7, vcc
	v_add_co_u32_e32 v20, vcc, s3, v6
	s_mov_b32 s3, 0x1a000
	s_nop 0
	v_addc_co_u32_e32 v21, vcc, 0, v7, vcc
	v_pk_add_f32 v[138:139], v[24:25], v[138:139]
	v_add_co_u32_e32 v24, vcc, s3, v6
	s_mov_b32 s3, 0x1c000
	s_nop 0
	v_addc_co_u32_e32 v25, vcc, 0, v7, vcc
	v_pk_add_f32 v[154:155], v[8:9], v[154:155]
	v_pk_add_f32 v[152:153], v[14:15], v[152:153]
	v_pk_add_f32 v[150:151], v[12:13], v[150:151]
	v_pk_add_f32 v[148:149], v[18:19], v[148:149]
	v_pk_add_f32 v[144:145], v[22:23], v[144:145]
	v_pk_add_f32 v[140:141], v[26:27], v[140:141]
	v_pk_add_f32 v[136:137], v[30:31], v[136:137]
	v_pk_add_f32 v[134:135], v[28:29], v[134:135]
	v_pk_add_f32 v[132:133], v[168:169], v[132:133]
	v_pk_add_f32 v[130:131], v[166:167], v[130:131]
	v_add_co_u32_e32 v28, vcc, s3, v6
	s_mov_b32 s3, 0x1e000
	s_nop 0
	v_addc_co_u32_e32 v29, vcc, 0, v7, vcc
	global_load_dwordx4 v[2:5], v[32:33], off
	global_load_dwordx4 v[8:11], v[170:171], off
	v_add_co_u32_e32 v32, vcc, s3, v6
	global_load_dwordx4 v[12:15], v[172:173], off
	s_nop 0
	global_load_dwordx4 v[16:19], v[16:17], off
	v_addc_co_u32_e32 v33, vcc, 0, v7, vcc
	global_load_dwordx4 v[20:23], v[20:21], off
	s_nop 0
	global_load_dwordx4 v[24:27], v[24:25], off
	s_mov_b32 s3, 0x20000
	global_load_dwordx4 v[28:31], v[28:29], off
	s_mov_b32 s6, 0x26000
	global_load_dwordx4 v[166:169], v[32:33], off
	v_add_co_u32_e32 v32, vcc, s3, v6
	s_mov_b32 s3, 0x30000
	s_nop 0
	v_addc_co_u32_e32 v33, vcc, 0, v7, vcc
	v_add_co_u32_e32 v170, vcc, s4, v6
	s_mov_b32 s4, 0x32000
	s_nop 0
	v_addc_co_u32_e32 v171, vcc, 0, v7, vcc
	v_add_co_u32_e32 v172, vcc, s5, v6
	s_mov_b32 s5, 0x34000
	s_nop 0
	v_addc_co_u32_e32 v173, vcc, 0, v7, vcc
	v_add_co_u32_e32 v174, vcc, s6, v6
	s_mov_b32 s6, 0x36000
	s_nop 0
	v_addc_co_u32_e32 v175, vcc, 0, v7, vcc
	v_add_co_u32_e32 v176, vcc, s7, v6
	s_mov_b32 s7, 0x38000
	s_nop 0
	v_addc_co_u32_e32 v177, vcc, 0, v7, vcc
	v_add_co_u32_e32 v178, vcc, s8, v6
	s_mov_b32 s8, 0x3a000
	s_nop 0
	v_addc_co_u32_e32 v179, vcc, 0, v7, vcc
	s_waitcnt vmcnt(0)
	v_pk_add_f32 v[128:129], v[4:5], v[128:129]
	v_pk_add_f32 v[126:127], v[2:3], v[126:127]
	v_pk_add_f32 v[124:125], v[10:11], v[124:125]
	v_pk_add_f32 v[122:123], v[8:9], v[122:123]
	v_pk_add_f32 v[120:121], v[14:15], v[120:121]
	v_pk_add_f32 v[118:119], v[12:13], v[118:119]
	v_pk_add_f32 v[116:117], v[18:19], v[116:117]
	v_pk_add_f32 v[114:115], v[16:17], v[114:115]
	v_pk_add_f32 v[112:113], v[22:23], v[112:113]
	v_pk_add_f32 v[110:111], v[20:21], v[110:111]
	v_pk_add_f32 v[108:109], v[26:27], v[108:109]
	v_pk_add_f32 v[106:107], v[24:25], v[106:107]
	v_pk_add_f32 v[104:105], v[30:31], v[104:105]
	v_pk_add_f32 v[102:103], v[28:29], v[102:103]
	v_pk_add_f32 v[100:101], v[168:169], v[100:101]
	v_pk_add_f32 v[98:99], v[166:167], v[98:99]
	v_add_co_u32_e32 v24, vcc, s9, v6
	global_load_dwordx4 v[2:5], v[32:33], off
	global_load_dwordx4 v[8:11], v[170:171], off
	global_load_dwordx4 v[12:15], v[172:173], off
	v_addc_co_u32_e32 v25, vcc, 0, v7, vcc
	global_load_dwordx4 v[16:19], v[174:175], off
	global_load_dwordx4 v[20:23], v[176:177], off
	global_load_dwordx4 v[30:33], v[178:179], off
	global_load_dwordx4 v[166:169], v[24:25], off
	v_add_co_u32_e32 v24, vcc, s10, v6
	s_mov_b32 s9, 0x3c000
	s_nop 0
	v_addc_co_u32_e32 v25, vcc, 0, v7, vcc
	global_load_dwordx4 v[170:173], v[24:25], off
	v_add_co_u32_e32 v24, vcc, s3, v6
	s_mov_b32 s10, 0x3e000
	s_nop 0
	v_addc_co_u32_e32 v25, vcc, 0, v7, vcc
	v_add_co_u32_e32 v174, vcc, s4, v6
	s_waitcnt vmcnt(0)
;     static __device__ __forceinline__ const void* rowptr(const void* b, size_t r, int ldc) { if constexpr (BASE_BF16) return (const bf16_t*)b + r * ldc; else return (const float*)b + r * ldc; }
;     static __device__ __forceinline__ void stq(bf16_t* p, f32x4 v) { u32x2 w; w.x = cvt_pk_bf16(v[0], v[1]); w.y = cvt_pk_bf16(v[2], v[3]); *(u32x2*)p = w; }
;     __device__ __forceinline__ void add_partial(f32x4 (&acc)[2][2][4][2], const Unit& u, int tid, int wid) const {
;     ...
;         for (int a = 0; a < 2; ++a)
; #pragma unroll
;             for (int b = 0; b < 2; ++b)
; #pragma unroll
;                 for (int m = 0; m < 4; ++m)
;                 {
; #pragma unroll
;                   for (int n = 0; n < 2; ++n) acc[a][b][m][n] += *(const f32x4*)(sp + ((size_t)((((a * 2 + b) * 4 + m) * 2 + n) * 512 + tid)) * 4);
;                   if (m == 3) asm volatile("" : "+v"(acc[a][b][0][0]), "+v"(acc[a][b][0][1]), "+v"(acc[a][b][1][0]), "+v"(acc[a][b][1][1]), "+v"(acc[a][b][2][0]), "+v"(acc[a][b][2][1]), "+v"(acc[a][b][3][0]), "+v"(acc[a][b][3][1]) :: "memory"); }
;     __device__ __forceinline__ void operator()(const f32x4 (&acc)[2][2][4][2], const Unit& u, int wr, int wc, int fr, int fq) const {
;     ...
;             for (int ai = 0; ai < 2; ++ai)
; #pragma unroll
;                 for (int m = 0; m < 4; ++m) { const int r = u.pm * BM + ai * HALF + wr * 64 + m * 16 + fr;
;                     const void* brow = (r < split_rows) ? rowptr(base_p, (size_t)r, ldc) : rowptr(base_s, (size_t)(r - split_rows), ldc);
;                     const float* grow = mod + (size_t)((r < split_rows) ? 0 : 1 + ((r - split_rows) >> 3)) * modld + goff;
;                     bf16_t* orow = out + (size_t)r * ldc;
; #pragma unroll
;                     for (int bj = 0; bj < 2; ++bj)
; #pragma unroll
;                         for (int n = 0; n < 2; ++n) { const int c = col0 + bj * HALF + n * 16;
;                             const f32x4 b = ldb(brow, c), g = *(const f32x4*)(grow + c);
;                             stq(orow + c, b + (g * gs) * acc[ai][bj][m][n]); }
;                     asm volatile("" ::: "memory"); }
	v_pk_add_f32 v[96:97], v[4:5], v[96:97]
	v_addc_co_u32_e32 v175, vcc, 0, v7, vcc
	v_add_co_u32_e32 v176, vcc, s5, v6
	v_pk_add_f32 v[90:91], v[8:9], v[90:91]
	s_nop 0
	v_addc_co_u32_e32 v177, vcc, 0, v7, vcc
	v_add_co_u32_e32 v178, vcc, s6, v6
	v_pk_add_f32 v[94:95], v[2:3], v[94:95]
	s_nop 0
	v_addc_co_u32_e32 v179, vcc, 0, v7, vcc
	v_add_co_u32_e32 v180, vcc, s7, v6
	v_pk_add_f32 v[92:93], v[10:11], v[92:93]
	s_nop 0
	v_addc_co_u32_e32 v181, vcc, 0, v7, vcc
	v_add_co_u32_e32 v182, vcc, s8, v6
	v_pk_add_f32 v[88:89], v[14:15], v[88:89]
	s_nop 0
	v_addc_co_u32_e32 v183, vcc, 0, v7, vcc
	v_add_co_u32_e32 v8, vcc, s9, v6
	v_pk_add_f32 v[86:87], v[12:13], v[86:87]
	s_nop 0
	v_addc_co_u32_e32 v9, vcc, 0, v7, vcc
	v_pk_add_f32 v[84:85], v[18:19], v[84:85]
	v_pk_add_f32 v[82:83], v[16:17], v[82:83]
	v_pk_add_f32 v[28:29], v[22:23], v[80:81]
	v_pk_add_f32 v[26:27], v[20:21], v[78:79]
	v_pk_add_f32 v[20:21], v[32:33], v[76:77]
	v_pk_add_f32 v[18:19], v[30:31], v[74:75]
	v_pk_add_f32 v[12:13], v[168:169], v[72:73]
	v_pk_add_f32 v[10:11], v[166:167], v[70:71]
	v_pk_add_f32 v[4:5], v[172:173], v[68:69]
	v_pk_add_f32 v[2:3], v[170:171], v[66:67]
	v_add_co_u32_e32 v6, vcc, s10, v6
	global_load_dwordx4 v[14:17], v[24:25], off
	s_nop 0
	global_load_dwordx4 v[22:25], v[174:175], off
	global_load_dwordx4 v[30:33], v[176:177], off
	v_addc_co_u32_e32 v7, vcc, 0, v7, vcc
	global_load_dwordx4 v[66:69], v[178:179], off
	global_load_dwordx4 v[70:73], v[180:181], off
	global_load_dwordx4 v[74:77], v[182:183], off
	global_load_dwordx4 v[78:81], v[8:9], off
	s_waitcnt vmcnt(0)
	v_pk_add_f32 v[64:65], v[16:17], v[64:65]
	global_load_dwordx4 v[6:9], v[6:7], off
	v_pk_add_f32 v[62:63], v[14:15], v[62:63]
	v_pk_add_f32 v[60:61], v[24:25], v[60:61]
	v_pk_add_f32 v[58:59], v[22:23], v[58:59]
	v_pk_add_f32 v[56:57], v[32:33], v[56:57]
	v_pk_add_f32 v[54:55], v[30:31], v[54:55]
	v_pk_add_f32 v[52:53], v[68:69], v[52:53]
	v_pk_add_f32 v[50:51], v[66:67], v[50:51]
	v_pk_add_f32 v[32:33], v[72:73], v[48:49]
	v_pk_add_f32 v[30:31], v[70:71], v[46:47]
	v_pk_add_f32 v[24:25], v[76:77], v[44:45]
	v_pk_add_f32 v[22:23], v[74:75], v[42:43]
	v_pk_add_f32 v[16:17], v[80:81], v[40:41]
	v_pk_add_f32 v[14:15], v[78:79], v[38:39]
	s_waitcnt vmcnt(0)
	v_pk_add_f32 v[8:9], v[8:9], v[36:37]
	v_pk_add_f32 v[6:7], v[6:7], v[34:35]
	v_or_b32_e32 v34, s1, v163
	v_lshl_or_b32 v1, s0, 8, v1
	v_or_b32_e32 v36, s21, v1
	s_add_u32 s10, s56, 0x20000
	s_addc_u32 s11, s57, 0
	s_mov_b32 s6, 0x24000
	s_mov_b32 s8, 0x39000000
	v_lshlrev_b32_e32 v35, 1, v36
	v_lshlrev_b32_e32 v37, 2, v36
	v_lshl_add_u32 v38, v34, 13, v35
	v_add_u32_e32 v46, 0xffffe000, v34
	v_ashrrev_i32_e32 v46, 3, v46
	v_add_u32_e32 v46, 1, v46
	v_max_i32_e32 v46, 0, v46
	v_mad_u32_u24 v66, v46, s6, v37
	v_add_u32_e32 v39, 0x20000, v38
	v_add_u32_e32 v46, 0xffffe010, v34
	v_ashrrev_i32_e32 v46, 3, v46
	v_add_u32_e32 v46, 1, v46
	v_max_i32_e32 v46, 0, v46
	v_mad_u32_u24 v67, v46, s6, v37
	v_add_u32_e32 v40, 0x40000, v38
	v_add_u32_e32 v46, 0xffffe020, v34
	v_ashrrev_i32_e32 v46, 3, v46
	v_add_u32_e32 v46, 1, v46
	v_max_i32_e32 v46, 0, v46
	v_mad_u32_u24 v68, v46, s6, v37
	v_add_u32_e32 v41, 0x60000, v38
	v_add_u32_e32 v46, 0xffffe030, v34
	v_ashrrev_i32_e32 v46, 3, v46
	v_add_u32_e32 v46, 1, v46
	v_max_i32_e32 v46, 0, v46
	v_mad_u32_u24 v69, v46, s6, v37
	v_add_u32_e32 v42, 0x100000, v38
	v_add_u32_e32 v46, 0xffffe080, v34
	v_ashrrev_i32_e32 v46, 3, v46
	v_add_u32_e32 v46, 1, v46
	v_max_i32_e32 v46, 0, v46
	v_mad_u32_u24 v70, v46, s6, v37
	v_add_u32_e32 v43, 0x120000, v38
	v_add_u32_e32 v46, 0xffffe090, v34
	v_ashrrev_i32_e32 v46, 3, v46
	v_add_u32_e32 v46, 1, v46
	v_max_i32_e32 v46, 0, v46
	v_mad_u32_u24 v71, v46, s6, v37
	v_add_u32_e32 v44, 0x140000, v38
	v_add_u32_e32 v46, 0xffffe0a0, v34
	v_ashrrev_i32_e32 v46, 3, v46
	v_add_u32_e32 v46, 1, v46
	v_max_i32_e32 v46, 0, v46
	v_mad_u32_u24 v72, v46, s6, v37
	v_add_u32_e32 v45, 0x160000, v38
	v_add_u32_e32 v46, 0xffffe0b0, v34
	v_ashrrev_i32_e32 v46, 3, v46
	v_add_u32_e32 v46, 1, v46
	v_max_i32_e32 v46, 0, v46
	v_mad_u32_u24 v73, v46, s6, v37
	global_load_dwordx2 v[166:167], v38, s[68:69]
	global_load_dwordx2 v[168:169], v38, s[68:69] offset:32
	global_load_dwordx2 v[170:171], v38, s[68:69] offset:256
	global_load_dwordx2 v[172:173], v38, s[68:69] offset:288
	global_load_dwordx4 v[174:177], v66, s[10:11]
	global_load_dwordx4 v[178:181], v66, s[10:11] offset:64
	global_load_dwordx4 v[182:185], v66, s[10:11] offset:512
	global_load_dwordx4 v[186:189], v66, s[10:11] offset:576
	global_load_dwordx2 v[190:191], v39, s[68:69]
	global_load_dwordx2 v[192:193], v39, s[68:69] offset:32
	global_load_dwordx2 v[194:195], v39, s[68:69] offset:256
	global_load_dwordx2 v[196:197], v39, s[68:69] offset:288
	global_load_dwordx4 v[198:201], v67, s[10:11]
	global_load_dwordx4 v[202:205], v67, s[10:11] offset:64
	global_load_dwordx4 v[206:209], v67, s[10:11] offset:512
	global_load_dwordx4 v[210:213], v67, s[10:11] offset:576
	s_waitcnt vmcnt(8)
;     static __device__ __forceinline__ const void* rowptr(const void* b, size_t r, int ldc) { if constexpr (BASE_BF16) return (const bf16_t*)b + r * ldc; else return (const float*)b + r * ldc; }
;     static __device__ __forceinline__ void stq(bf16_t* p, f32x4 v) { u32x2 w; w.x = cvt_pk_bf16(v[0], v[1]); w.y = cvt_pk_bf16(v[2], v[3]); *(u32x2*)p = w; }
;     __device__ __forceinline__ void operator()(const f32x4 (&acc)[2][2][4][2], const Unit& u, int wr, int wc, int fr, int fq) const {
;     ...
;             for (int ai = 0; ai < 2; ++ai)
; #pragma unroll
;                 for (int m = 0; m < 4; ++m) { const int r = u.pm * BM + ai * HALF + wr * 64 + m * 16 + fr;
;                     const void* brow = (r < split_rows) ? rowptr(base_p, (size_t)r, ldc) : rowptr(base_s, (size_t)(r - split_rows), ldc);
;                     const float* grow = mod + (size_t)((r < split_rows) ? 0 : 1 + ((r - split_rows) >> 3)) * modld + goff;
;                     bf16_t* orow = out + (size_t)r * ldc;
; #pragma unroll
;                     for (int bj = 0; bj < 2; ++bj)
; #pragma unroll
;                         for (int n = 0; n < 2; ++n) { const int c = col0 + bj * HALF + n * 16;
;                             const f32x4 b = ldb(brow, c), g = *(const f32x4*)(grow + c);
;                             stq(orow + c, b + (g * gs) * acc[ai][bj][m][n]); }
;                     asm volatile("" ::: "memory"); }
	v_lshlrev_b32_e32 v74, 16, v166
	v_and_b32_e32 v75, 0xffff0000, v166
	v_pk_mul_f32 v[174:175], v[174:175], s[8:9] op_sel_hi:[1,0]
	v_lshlrev_b32_e32 v76, 16, v167
	v_and_b32_e32 v77, 0xffff0000, v167
	v_pk_mul_f32 v[176:177], v[176:177], s[8:9] op_sel_hi:[1,0]
	v_pk_fma_f32 v[74:75], v[174:175], v[158:159], v[74:75]
	v_pk_fma_f32 v[76:77], v[176:177], v[160:161], v[76:77]
	v_cvt_pk_bf16_f32 v48, v74, v75
	v_cvt_pk_bf16_f32 v49, v76, v77
	global_store_dwordx2 v38, v[48:49], s[68:69]
	v_lshlrev_b32_e32 v74, 16, v168
	v_and_b32_e32 v75, 0xffff0000, v168
	v_pk_mul_f32 v[178:179], v[178:179], s[8:9] op_sel_hi:[1,0]
	v_lshlrev_b32_e32 v76, 16, v169
	v_and_b32_e32 v77, 0xffff0000, v169
	v_pk_mul_f32 v[180:181], v[180:181], s[8:9] op_sel_hi:[1,0]
	v_pk_fma_f32 v[74:75], v[178:179], v[154:155], v[74:75]
	v_pk_fma_f32 v[76:77], v[180:181], v[156:157], v[76:77]
	v_cvt_pk_bf16_f32 v48, v74, v75
	v_cvt_pk_bf16_f32 v49, v76, v77
	global_store_dwordx2 v38, v[48:49], s[68:69] offset:32
	v_lshlrev_b32_e32 v74, 16, v170
	v_and_b32_e32 v75, 0xffff0000, v170
	v_pk_mul_f32 v[182:183], v[182:183], s[8:9] op_sel_hi:[1,0]
	v_lshlrev_b32_e32 v76, 16, v171
	v_and_b32_e32 v77, 0xffff0000, v171
	v_pk_mul_f32 v[184:185], v[184:185], s[8:9] op_sel_hi:[1,0]
	v_pk_fma_f32 v[74:75], v[182:183], v[126:127], v[74:75]
	v_pk_fma_f32 v[76:77], v[184:185], v[128:129], v[76:77]
	v_cvt_pk_bf16_f32 v48, v74, v75
	v_cvt_pk_bf16_f32 v49, v76, v77
	global_store_dwordx2 v38, v[48:49], s[68:69] offset:256
	v_lshlrev_b32_e32 v74, 16, v172
	v_and_b32_e32 v75, 0xffff0000, v172
	v_pk_mul_f32 v[186:187], v[186:187], s[8:9] op_sel_hi:[1,0]
	v_lshlrev_b32_e32 v76, 16, v173
	v_and_b32_e32 v77, 0xffff0000, v173
	v_pk_mul_f32 v[188:189], v[188:189], s[8:9] op_sel_hi:[1,0]
	v_pk_fma_f32 v[74:75], v[186:187], v[122:123], v[74:75]
	v_pk_fma_f32 v[76:77], v[188:189], v[124:125], v[76:77]
	v_cvt_pk_bf16_f32 v48, v74, v75
	v_cvt_pk_bf16_f32 v49, v76, v77
	global_store_dwordx2 v38, v[48:49], s[68:69] offset:288
	global_load_dwordx2 v[166:167], v40, s[68:69]
	global_load_dwordx2 v[168:169], v40, s[68:69] offset:32
	global_load_dwordx2 v[170:171], v40, s[68:69] offset:256
	global_load_dwordx2 v[172:173], v40, s[68:69] offset:288
	global_load_dwordx4 v[174:177], v68, s[10:11]
	global_load_dwordx4 v[178:181], v68, s[10:11] offset:64
	global_load_dwordx4 v[182:185], v68, s[10:11] offset:512
	global_load_dwordx4 v[186:189], v68, s[10:11] offset:576
	s_waitcnt vmcnt(12)
	v_lshlrev_b32_e32 v74, 16, v190
	v_and_b32_e32 v75, 0xffff0000, v190
	v_pk_mul_f32 v[198:199], v[198:199], s[8:9] op_sel_hi:[1,0]
	v_lshlrev_b32_e32 v76, 16, v191
	v_and_b32_e32 v77, 0xffff0000, v191
	v_pk_mul_f32 v[200:201], v[200:201], s[8:9] op_sel_hi:[1,0]
	v_pk_fma_f32 v[74:75], v[198:199], v[150:151], v[74:75]
	v_pk_fma_f32 v[76:77], v[200:201], v[152:153], v[76:77]
	v_cvt_pk_bf16_f32 v48, v74, v75
	v_cvt_pk_bf16_f32 v49, v76, v77
	global_store_dwordx2 v39, v[48:49], s[68:69]
	v_lshlrev_b32_e32 v74, 16, v192
	v_and_b32_e32 v75, 0xffff0000, v192
	v_pk_mul_f32 v[202:203], v[202:203], s[8:9] op_sel_hi:[1,0]
	v_lshlrev_b32_e32 v76, 16, v193
	v_and_b32_e32 v77, 0xffff0000, v193
	v_pk_mul_f32 v[204:205], v[204:205], s[8:9] op_sel_hi:[1,0]
	v_pk_fma_f32 v[74:75], v[202:203], v[146:147], v[74:75]
	v_pk_fma_f32 v[76:77], v[204:205], v[148:149], v[76:77]
	v_cvt_pk_bf16_f32 v48, v74, v75
	v_cvt_pk_bf16_f32 v49, v76, v77
	global_store_dwordx2 v39, v[48:49], s[68:69] offset:32
	v_lshlrev_b32_e32 v74, 16, v194
	v_and_b32_e32 v75, 0xffff0000, v194
	v_pk_mul_f32 v[206:207], v[206:207], s[8:9] op_sel_hi:[1,0]
	v_lshlrev_b32_e32 v76, 16, v195
	v_and_b32_e32 v77, 0xffff0000, v195
	v_pk_mul_f32 v[208:209], v[208:209], s[8:9] op_sel_hi:[1,0]
	v_pk_fma_f32 v[74:75], v[206:207], v[118:119], v[74:75]
	v_pk_fma_f32 v[76:77], v[208:209], v[120:121], v[76:77]
	v_cvt_pk_bf16_f32 v48, v74, v75
	v_cvt_pk_bf16_f32 v49, v76, v77
	global_store_dwordx2 v39, v[48:49], s[68:69] offset:256
	v_lshlrev_b32_e32 v74, 16, v196
	v_and_b32_e32 v75, 0xffff0000, v196
	v_pk_mul_f32 v[210:211], v[210:211], s[8:9] op_sel_hi:[1,0]
	v_lshlrev_b32_e32 v76, 16, v197
	v_and_b32_e32 v77, 0xffff0000, v197
	v_pk_mul_f32 v[212:213], v[212:213], s[8:9] op_sel_hi:[1,0]
	v_pk_fma_f32 v[74:75], v[210:211], v[114:115], v[74:75]
	v_pk_fma_f32 v[76:77], v[212:213], v[116:117], v[76:77]
	v_cvt_pk_bf16_f32 v48, v74, v75
	v_cvt_pk_bf16_f32 v49, v76, v77
	global_store_dwordx2 v39, v[48:49], s[68:69] offset:288
	global_load_dwordx2 v[190:191], v41, s[68:69]
	global_load_dwordx2 v[192:193], v41, s[68:69] offset:32
	global_load_dwordx2 v[194:195], v41, s[68:69] offset:256
	global_load_dwordx2 v[196:197], v41, s[68:69] offset:288
	global_load_dwordx4 v[198:201], v69, s[10:11]
	global_load_dwordx4 v[202:205], v69, s[10:11] offset:64
	global_load_dwordx4 v[206:209], v69, s[10:11] offset:512
	global_load_dwordx4 v[210:213], v69, s[10:11] offset:576
	s_waitcnt vmcnt(12)
;     static __device__ __forceinline__ const void* rowptr(const void* b, size_t r, int ldc) { if constexpr (BASE_BF16) return (const bf16_t*)b + r * ldc; else return (const float*)b + r * ldc; }
;     static __device__ __forceinline__ void stq(bf16_t* p, f32x4 v) { u32x2 w; w.x = cvt_pk_bf16(v[0], v[1]); w.y = cvt_pk_bf16(v[2], v[3]); *(u32x2*)p = w; }
;     __device__ __forceinline__ void operator()(const f32x4 (&acc)[2][2][4][2], const Unit& u, int wr, int wc, int fr, int fq) const {
;     ...
;             for (int ai = 0; ai < 2; ++ai)
; #pragma unroll
;                 for (int m = 0; m < 4; ++m) { const int r = u.pm * BM + ai * HALF + wr * 64 + m * 16 + fr;
;                     const void* brow = (r < split_rows) ? rowptr(base_p, (size_t)r, ldc) : rowptr(base_s, (size_t)(r - split_rows), ldc);
;                     const float* grow = mod + (size_t)((r < split_rows) ? 0 : 1 + ((r - split_rows) >> 3)) * modld + goff;
;                     bf16_t* orow = out + (size_t)r * ldc;
; #pragma unroll
;                     for (int bj = 0; bj < 2; ++bj)
; #pragma unroll
;                         for (int n = 0; n < 2; ++n) { const int c = col0 + bj * HALF + n * 16;
;                             const f32x4 b = ldb(brow, c), g = *(const f32x4*)(grow + c);
;                             stq(orow + c, b + (g * gs) * acc[ai][bj][m][n]); }
;                     asm volatile("" ::: "memory"); }
	v_lshlrev_b32_e32 v74, 16, v166
	v_and_b32_e32 v75, 0xffff0000, v166
	v_pk_mul_f32 v[174:175], v[174:175], s[8:9] op_sel_hi:[1,0]
	v_lshlrev_b32_e32 v76, 16, v167
	v_and_b32_e32 v77, 0xffff0000, v167
	v_pk_mul_f32 v[176:177], v[176:177], s[8:9] op_sel_hi:[1,0]
	v_pk_fma_f32 v[74:75], v[174:175], v[142:143], v[74:75]
	v_pk_fma_f32 v[76:77], v[176:177], v[144:145], v[76:77]
	v_cvt_pk_bf16_f32 v48, v74, v75
	v_cvt_pk_bf16_f32 v49, v76, v77
	global_store_dwordx2 v40, v[48:49], s[68:69]
	v_lshlrev_b32_e32 v74, 16, v168
	v_and_b32_e32 v75, 0xffff0000, v168
	v_pk_mul_f32 v[178:179], v[178:179], s[8:9] op_sel_hi:[1,0]
	v_lshlrev_b32_e32 v76, 16, v169
	v_and_b32_e32 v77, 0xffff0000, v169
	v_pk_mul_f32 v[180:181], v[180:181], s[8:9] op_sel_hi:[1,0]
	v_pk_fma_f32 v[74:75], v[178:179], v[138:139], v[74:75]
	v_pk_fma_f32 v[76:77], v[180:181], v[140:141], v[76:77]
	v_cvt_pk_bf16_f32 v48, v74, v75
	v_cvt_pk_bf16_f32 v49, v76, v77
	global_store_dwordx2 v40, v[48:49], s[68:69] offset:32
	v_lshlrev_b32_e32 v74, 16, v170
	v_and_b32_e32 v75, 0xffff0000, v170
	v_pk_mul_f32 v[182:183], v[182:183], s[8:9] op_sel_hi:[1,0]
	v_lshlrev_b32_e32 v76, 16, v171
	v_and_b32_e32 v77, 0xffff0000, v171
	v_pk_mul_f32 v[184:185], v[184:185], s[8:9] op_sel_hi:[1,0]
	v_pk_fma_f32 v[74:75], v[182:183], v[110:111], v[74:75]
	v_pk_fma_f32 v[76:77], v[184:185], v[112:113], v[76:77]
	v_cvt_pk_bf16_f32 v48, v74, v75
	v_cvt_pk_bf16_f32 v49, v76, v77
	global_store_dwordx2 v40, v[48:49], s[68:69] offset:256
	v_lshlrev_b32_e32 v74, 16, v172
	v_and_b32_e32 v75, 0xffff0000, v172
	v_pk_mul_f32 v[186:187], v[186:187], s[8:9] op_sel_hi:[1,0]
	v_lshlrev_b32_e32 v76, 16, v173
	v_and_b32_e32 v77, 0xffff0000, v173
	v_pk_mul_f32 v[188:189], v[188:189], s[8:9] op_sel_hi:[1,0]
	v_pk_fma_f32 v[74:75], v[186:187], v[106:107], v[74:75]
	v_pk_fma_f32 v[76:77], v[188:189], v[108:109], v[76:77]
	v_cvt_pk_bf16_f32 v48, v74, v75
	v_cvt_pk_bf16_f32 v49, v76, v77
	global_store_dwordx2 v40, v[48:49], s[68:69] offset:288
	global_load_dwordx2 v[166:167], v42, s[68:69]
	global_load_dwordx2 v[168:169], v42, s[68:69] offset:32
	global_load_dwordx2 v[170:171], v42, s[68:69] offset:256
	global_load_dwordx2 v[172:173], v42, s[68:69] offset:288
	global_load_dwordx4 v[174:177], v70, s[10:11]
	global_load_dwordx4 v[178:181], v70, s[10:11] offset:64
	global_load_dwordx4 v[182:185], v70, s[10:11] offset:512
	global_load_dwordx4 v[186:189], v70, s[10:11] offset:576
	s_waitcnt vmcnt(12)
	v_lshlrev_b32_e32 v74, 16, v190
	v_and_b32_e32 v75, 0xffff0000, v190
	v_pk_mul_f32 v[198:199], v[198:199], s[8:9] op_sel_hi:[1,0]
	v_lshlrev_b32_e32 v76, 16, v191
	v_and_b32_e32 v77, 0xffff0000, v191
	v_pk_mul_f32 v[200:201], v[200:201], s[8:9] op_sel_hi:[1,0]
	v_pk_fma_f32 v[74:75], v[198:199], v[134:135], v[74:75]
	v_pk_fma_f32 v[76:77], v[200:201], v[136:137], v[76:77]
	v_cvt_pk_bf16_f32 v48, v74, v75
	v_cvt_pk_bf16_f32 v49, v76, v77
	global_store_dwordx2 v41, v[48:49], s[68:69]
	v_lshlrev_b32_e32 v74, 16, v192
	v_and_b32_e32 v75, 0xffff0000, v192
	v_pk_mul_f32 v[202:203], v[202:203], s[8:9] op_sel_hi:[1,0]
	v_lshlrev_b32_e32 v76, 16, v193
	v_and_b32_e32 v77, 0xffff0000, v193
	v_pk_mul_f32 v[204:205], v[204:205], s[8:9] op_sel_hi:[1,0]
	v_pk_fma_f32 v[74:75], v[202:203], v[130:131], v[74:75]
	v_pk_fma_f32 v[76:77], v[204:205], v[132:133], v[76:77]
	v_cvt_pk_bf16_f32 v48, v74, v75
	v_cvt_pk_bf16_f32 v49, v76, v77
	global_store_dwordx2 v41, v[48:49], s[68:69] offset:32
	v_lshlrev_b32_e32 v74, 16, v194
	v_and_b32_e32 v75, 0xffff0000, v194
	v_pk_mul_f32 v[206:207], v[206:207], s[8:9] op_sel_hi:[1,0]
	v_lshlrev_b32_e32 v76, 16, v195
	v_and_b32_e32 v77, 0xffff0000, v195
	v_pk_mul_f32 v[208:209], v[208:209], s[8:9] op_sel_hi:[1,0]
	v_pk_fma_f32 v[74:75], v[206:207], v[102:103], v[74:75]
	v_pk_fma_f32 v[76:77], v[208:209], v[104:105], v[76:77]
	v_cvt_pk_bf16_f32 v48, v74, v75
	v_cvt_pk_bf16_f32 v49, v76, v77
	global_store_dwordx2 v41, v[48:49], s[68:69] offset:256
	v_lshlrev_b32_e32 v74, 16, v196
	v_and_b32_e32 v75, 0xffff0000, v196
	v_pk_mul_f32 v[210:211], v[210:211], s[8:9] op_sel_hi:[1,0]
	v_lshlrev_b32_e32 v76, 16, v197
	v_and_b32_e32 v77, 0xffff0000, v197
	v_pk_mul_f32 v[212:213], v[212:213], s[8:9] op_sel_hi:[1,0]
	v_pk_fma_f32 v[74:75], v[210:211], v[98:99], v[74:75]
	v_pk_fma_f32 v[76:77], v[212:213], v[100:101], v[76:77]
	v_cvt_pk_bf16_f32 v48, v74, v75
	v_cvt_pk_bf16_f32 v49, v76, v77
	global_store_dwordx2 v41, v[48:49], s[68:69] offset:288
	global_load_dwordx2 v[190:191], v43, s[68:69]
	global_load_dwordx2 v[192:193], v43, s[68:69] offset:32
	global_load_dwordx2 v[194:195], v43, s[68:69] offset:256
	global_load_dwordx2 v[196:197], v43, s[68:69] offset:288
	global_load_dwordx4 v[198:201], v71, s[10:11]
	global_load_dwordx4 v[202:205], v71, s[10:11] offset:64
	global_load_dwordx4 v[206:209], v71, s[10:11] offset:512
	global_load_dwordx4 v[210:213], v71, s[10:11] offset:576
	s_waitcnt vmcnt(12)
;     static __device__ __forceinline__ const void* rowptr(const void* b, size_t r, int ldc) { if constexpr (BASE_BF16) return (const bf16_t*)b + r * ldc; else return (const float*)b + r * ldc; }
;     static __device__ __forceinline__ void stq(bf16_t* p, f32x4 v) { u32x2 w; w.x = cvt_pk_bf16(v[0], v[1]); w.y = cvt_pk_bf16(v[2], v[3]); *(u32x2*)p = w; }
;     __device__ __forceinline__ void operator()(const f32x4 (&acc)[2][2][4][2], const Unit& u, int wr, int wc, int fr, int fq) const {
;     ...
;             for (int ai = 0; ai < 2; ++ai)
; #pragma unroll
;                 for (int m = 0; m < 4; ++m) { const int r = u.pm * BM + ai * HALF + wr * 64 + m * 16 + fr;
;                     const void* brow = (r < split_rows) ? rowptr(base_p, (size_t)r, ldc) : rowptr(base_s, (size_t)(r - split_rows), ldc);
;                     const float* grow = mod + (size_t)((r < split_rows) ? 0 : 1 + ((r - split_rows) >> 3)) * modld + goff;
;                     bf16_t* orow = out + (size_t)r * ldc;
; #pragma unroll
;                     for (int bj = 0; bj < 2; ++bj)
; #pragma unroll
;                         for (int n = 0; n < 2; ++n) { const int c = col0 + bj * HALF + n * 16;
;                             const f32x4 b = ldb(brow, c), g = *(const f32x4*)(grow + c);
;                             stq(orow + c, b + (g * gs) * acc[ai][bj][m][n]); }
;                     asm volatile("" ::: "memory"); }
	v_lshlrev_b32_e32 v74, 16, v166
	v_and_b32_e32 v75, 0xffff0000, v166
	v_pk_mul_f32 v[174:175], v[174:175], s[8:9] op_sel_hi:[1,0]
	v_lshlrev_b32_e32 v76, 16, v167
	v_and_b32_e32 v77, 0xffff0000, v167
	v_pk_mul_f32 v[176:177], v[176:177], s[8:9] op_sel_hi:[1,0]
	v_pk_fma_f32 v[74:75], v[174:175], v[94:95], v[74:75]
	v_pk_fma_f32 v[76:77], v[176:177], v[96:97], v[76:77]
	v_cvt_pk_bf16_f32 v48, v74, v75
	v_cvt_pk_bf16_f32 v49, v76, v77
	global_store_dwordx2 v42, v[48:49], s[68:69]
	v_lshlrev_b32_e32 v74, 16, v168
	v_and_b32_e32 v75, 0xffff0000, v168
	v_pk_mul_f32 v[178:179], v[178:179], s[8:9] op_sel_hi:[1,0]
	v_lshlrev_b32_e32 v76, 16, v169
	v_and_b32_e32 v77, 0xffff0000, v169
	v_pk_mul_f32 v[180:181], v[180:181], s[8:9] op_sel_hi:[1,0]
	v_pk_fma_f32 v[74:75], v[178:179], v[90:91], v[74:75]
	v_pk_fma_f32 v[76:77], v[180:181], v[92:93], v[76:77]
	v_cvt_pk_bf16_f32 v48, v74, v75
	v_cvt_pk_bf16_f32 v49, v76, v77
	global_store_dwordx2 v42, v[48:49], s[68:69] offset:32
	v_lshlrev_b32_e32 v74, 16, v170
	v_and_b32_e32 v75, 0xffff0000, v170
	v_pk_mul_f32 v[182:183], v[182:183], s[8:9] op_sel_hi:[1,0]
	v_lshlrev_b32_e32 v76, 16, v171
	v_and_b32_e32 v77, 0xffff0000, v171
	v_pk_mul_f32 v[184:185], v[184:185], s[8:9] op_sel_hi:[1,0]
	v_pk_fma_f32 v[74:75], v[182:183], v[62:63], v[74:75]
	v_pk_fma_f32 v[76:77], v[184:185], v[64:65], v[76:77]
	v_cvt_pk_bf16_f32 v48, v74, v75
	v_cvt_pk_bf16_f32 v49, v76, v77
	global_store_dwordx2 v42, v[48:49], s[68:69] offset:256
	v_lshlrev_b32_e32 v74, 16, v172
	v_and_b32_e32 v75, 0xffff0000, v172
	v_pk_mul_f32 v[186:187], v[186:187], s[8:9] op_sel_hi:[1,0]
	v_lshlrev_b32_e32 v76, 16, v173
	v_and_b32_e32 v77, 0xffff0000, v173
	v_pk_mul_f32 v[188:189], v[188:189], s[8:9] op_sel_hi:[1,0]
	v_pk_fma_f32 v[74:75], v[186:187], v[58:59], v[74:75]
	v_pk_fma_f32 v[76:77], v[188:189], v[60:61], v[76:77]
	v_cvt_pk_bf16_f32 v48, v74, v75
	v_cvt_pk_bf16_f32 v49, v76, v77
	global_store_dwordx2 v42, v[48:49], s[68:69] offset:288
	global_load_dwordx2 v[166:167], v44, s[68:69]
	global_load_dwordx2 v[168:169], v44, s[68:69] offset:32
	global_load_dwordx2 v[170:171], v44, s[68:69] offset:256
	global_load_dwordx2 v[172:173], v44, s[68:69] offset:288
	global_load_dwordx4 v[174:177], v72, s[10:11]
	global_load_dwordx4 v[178:181], v72, s[10:11] offset:64
	global_load_dwordx4 v[182:185], v72, s[10:11] offset:512
	global_load_dwordx4 v[186:189], v72, s[10:11] offset:576
	s_waitcnt vmcnt(12)
	v_lshlrev_b32_e32 v74, 16, v190
	v_and_b32_e32 v75, 0xffff0000, v190
	v_pk_mul_f32 v[198:199], v[198:199], s[8:9] op_sel_hi:[1,0]
	v_lshlrev_b32_e32 v76, 16, v191
	v_and_b32_e32 v77, 0xffff0000, v191
	v_pk_mul_f32 v[200:201], v[200:201], s[8:9] op_sel_hi:[1,0]
	v_pk_fma_f32 v[74:75], v[198:199], v[86:87], v[74:75]
	v_pk_fma_f32 v[76:77], v[200:201], v[88:89], v[76:77]
	v_cvt_pk_bf16_f32 v48, v74, v75
	v_cvt_pk_bf16_f32 v49, v76, v77
	global_store_dwordx2 v43, v[48:49], s[68:69]
	v_lshlrev_b32_e32 v74, 16, v192
	v_and_b32_e32 v75, 0xffff0000, v192
	v_pk_mul_f32 v[202:203], v[202:203], s[8:9] op_sel_hi:[1,0]
	v_lshlrev_b32_e32 v76, 16, v193
	v_and_b32_e32 v77, 0xffff0000, v193
	v_pk_mul_f32 v[204:205], v[204:205], s[8:9] op_sel_hi:[1,0]
	v_pk_fma_f32 v[74:75], v[202:203], v[82:83], v[74:75]
	v_pk_fma_f32 v[76:77], v[204:205], v[84:85], v[76:77]
	v_cvt_pk_bf16_f32 v48, v74, v75
	v_cvt_pk_bf16_f32 v49, v76, v77
	global_store_dwordx2 v43, v[48:49], s[68:69] offset:32
	v_lshlrev_b32_e32 v74, 16, v194
	v_and_b32_e32 v75, 0xffff0000, v194
	v_pk_mul_f32 v[206:207], v[206:207], s[8:9] op_sel_hi:[1,0]
	v_lshlrev_b32_e32 v76, 16, v195
	v_and_b32_e32 v77, 0xffff0000, v195
	v_pk_mul_f32 v[208:209], v[208:209], s[8:9] op_sel_hi:[1,0]
	v_pk_fma_f32 v[74:75], v[206:207], v[54:55], v[74:75]
	v_pk_fma_f32 v[76:77], v[208:209], v[56:57], v[76:77]
	v_cvt_pk_bf16_f32 v48, v74, v75
	v_cvt_pk_bf16_f32 v49, v76, v77
	global_store_dwordx2 v43, v[48:49], s[68:69] offset:256
	v_lshlrev_b32_e32 v74, 16, v196
	v_and_b32_e32 v75, 0xffff0000, v196
	v_pk_mul_f32 v[210:211], v[210:211], s[8:9] op_sel_hi:[1,0]
	v_lshlrev_b32_e32 v76, 16, v197
	v_and_b32_e32 v77, 0xffff0000, v197
	v_pk_mul_f32 v[212:213], v[212:213], s[8:9] op_sel_hi:[1,0]
	v_pk_fma_f32 v[74:75], v[210:211], v[50:51], v[74:75]
	v_pk_fma_f32 v[76:77], v[212:213], v[52:53], v[76:77]
	v_cvt_pk_bf16_f32 v48, v74, v75
	v_cvt_pk_bf16_f32 v49, v76, v77
	global_store_dwordx2 v43, v[48:49], s[68:69] offset:288
	global_load_dwordx2 v[190:191], v45, s[68:69]
	global_load_dwordx2 v[192:193], v45, s[68:69] offset:32
	global_load_dwordx2 v[194:195], v45, s[68:69] offset:256
	global_load_dwordx2 v[196:197], v45, s[68:69] offset:288
	global_load_dwordx4 v[198:201], v73, s[10:11]
	global_load_dwordx4 v[202:205], v73, s[10:11] offset:64
	global_load_dwordx4 v[206:209], v73, s[10:11] offset:512
	global_load_dwordx4 v[210:213], v73, s[10:11] offset:576
	s_waitcnt vmcnt(12)
;     static __device__ __forceinline__ const void* rowptr(const void* b, size_t r, int ldc) { if constexpr (BASE_BF16) return (const bf16_t*)b + r * ldc; else return (const float*)b + r * ldc; }
;     static __device__ __forceinline__ void stq(bf16_t* p, f32x4 v) { u32x2 w; w.x = cvt_pk_bf16(v[0], v[1]); w.y = cvt_pk_bf16(v[2], v[3]); *(u32x2*)p = w; }
;     __device__ __forceinline__ void operator()(const f32x4 (&acc)[2][2][4][2], const Unit& u, int wr, int wc, int fr, int fq) const {
;     ...
;             for (int ai = 0; ai < 2; ++ai)
; #pragma unroll
;                 for (int m = 0; m < 4; ++m) { const int r = u.pm * BM + ai * HALF + wr * 64 + m * 16 + fr;
;                     const void* brow = (r < split_rows) ? rowptr(base_p, (size_t)r, ldc) : rowptr(base_s, (size_t)(r - split_rows), ldc);
;                     const float* grow = mod + (size_t)((r < split_rows) ? 0 : 1 + ((r - split_rows) >> 3)) * modld + goff;
;                     bf16_t* orow = out + (size_t)r * ldc;
; #pragma unroll
;                     for (int bj = 0; bj < 2; ++bj)
; #pragma unroll
;                         for (int n = 0; n < 2; ++n) { const int c = col0 + bj * HALF + n * 16;
;                             const f32x4 b = ldb(brow, c), g = *(const f32x4*)(grow + c);
;                             stq(orow + c, b + (g * gs) * acc[ai][bj][m][n]); }
;                     asm volatile("" ::: "memory"); }
	v_lshlrev_b32_e32 v74, 16, v166
	v_and_b32_e32 v75, 0xffff0000, v166
	v_pk_mul_f32 v[174:175], v[174:175], s[8:9] op_sel_hi:[1,0]
	v_lshlrev_b32_e32 v76, 16, v167
	v_and_b32_e32 v77, 0xffff0000, v167
	v_pk_mul_f32 v[176:177], v[176:177], s[8:9] op_sel_hi:[1,0]
	v_pk_fma_f32 v[74:75], v[174:175], v[26:27], v[74:75]
	v_pk_fma_f32 v[76:77], v[176:177], v[28:29], v[76:77]
	v_cvt_pk_bf16_f32 v48, v74, v75
	v_cvt_pk_bf16_f32 v49, v76, v77
	global_store_dwordx2 v44, v[48:49], s[68:69]
	v_lshlrev_b32_e32 v74, 16, v168
	v_and_b32_e32 v75, 0xffff0000, v168
	v_pk_mul_f32 v[178:179], v[178:179], s[8:9] op_sel_hi:[1,0]
	v_lshlrev_b32_e32 v76, 16, v169
	v_and_b32_e32 v77, 0xffff0000, v169
	v_pk_mul_f32 v[180:181], v[180:181], s[8:9] op_sel_hi:[1,0]
	v_pk_fma_f32 v[74:75], v[178:179], v[18:19], v[74:75]
	v_pk_fma_f32 v[76:77], v[180:181], v[20:21], v[76:77]
	v_cvt_pk_bf16_f32 v48, v74, v75
	v_cvt_pk_bf16_f32 v49, v76, v77
	global_store_dwordx2 v44, v[48:49], s[68:69] offset:32
	v_lshlrev_b32_e32 v74, 16, v170
	v_and_b32_e32 v75, 0xffff0000, v170
	v_pk_mul_f32 v[182:183], v[182:183], s[8:9] op_sel_hi:[1,0]
	v_lshlrev_b32_e32 v76, 16, v171
	v_and_b32_e32 v77, 0xffff0000, v171
	v_pk_mul_f32 v[184:185], v[184:185], s[8:9] op_sel_hi:[1,0]
	v_pk_fma_f32 v[74:75], v[182:183], v[30:31], v[74:75]
	v_pk_fma_f32 v[76:77], v[184:185], v[32:33], v[76:77]
	v_cvt_pk_bf16_f32 v48, v74, v75
	v_cvt_pk_bf16_f32 v49, v76, v77
	global_store_dwordx2 v44, v[48:49], s[68:69] offset:256
	v_lshlrev_b32_e32 v74, 16, v172
	v_and_b32_e32 v75, 0xffff0000, v172
	v_pk_mul_f32 v[186:187], v[186:187], s[8:9] op_sel_hi:[1,0]
	v_lshlrev_b32_e32 v76, 16, v173
	v_and_b32_e32 v77, 0xffff0000, v173
	v_pk_mul_f32 v[188:189], v[188:189], s[8:9] op_sel_hi:[1,0]
	v_pk_fma_f32 v[74:75], v[186:187], v[22:23], v[74:75]
	v_pk_fma_f32 v[76:77], v[188:189], v[24:25], v[76:77]
	v_cvt_pk_bf16_f32 v48, v74, v75
	v_cvt_pk_bf16_f32 v49, v76, v77
	global_store_dwordx2 v44, v[48:49], s[68:69] offset:288
	s_waitcnt vmcnt(4)
	v_lshlrev_b32_e32 v74, 16, v190
	v_and_b32_e32 v75, 0xffff0000, v190
	v_pk_mul_f32 v[198:199], v[198:199], s[8:9] op_sel_hi:[1,0]
	v_lshlrev_b32_e32 v76, 16, v191
	v_and_b32_e32 v77, 0xffff0000, v191
	v_pk_mul_f32 v[200:201], v[200:201], s[8:9] op_sel_hi:[1,0]
	v_pk_fma_f32 v[74:75], v[198:199], v[10:11], v[74:75]
	v_pk_fma_f32 v[76:77], v[200:201], v[12:13], v[76:77]
	v_cvt_pk_bf16_f32 v48, v74, v75
	v_cvt_pk_bf16_f32 v49, v76, v77
	global_store_dwordx2 v45, v[48:49], s[68:69]
	v_lshlrev_b32_e32 v74, 16, v192
	v_and_b32_e32 v75, 0xffff0000, v192
	v_pk_mul_f32 v[202:203], v[202:203], s[8:9] op_sel_hi:[1,0]
	v_lshlrev_b32_e32 v76, 16, v193
	v_and_b32_e32 v77, 0xffff0000, v193
	v_pk_mul_f32 v[204:205], v[204:205], s[8:9] op_sel_hi:[1,0]
	v_pk_fma_f32 v[74:75], v[202:203], v[2:3], v[74:75]
	v_pk_fma_f32 v[76:77], v[204:205], v[4:5], v[76:77]
	v_cvt_pk_bf16_f32 v48, v74, v75
	v_cvt_pk_bf16_f32 v49, v76, v77
	global_store_dwordx2 v45, v[48:49], s[68:69] offset:32
	v_lshlrev_b32_e32 v74, 16, v194
	v_and_b32_e32 v75, 0xffff0000, v194
	v_pk_mul_f32 v[206:207], v[206:207], s[8:9] op_sel_hi:[1,0]
	v_lshlrev_b32_e32 v76, 16, v195
	v_and_b32_e32 v77, 0xffff0000, v195
	v_pk_mul_f32 v[208:209], v[208:209], s[8:9] op_sel_hi:[1,0]
	v_pk_fma_f32 v[74:75], v[206:207], v[14:15], v[74:75]
	v_pk_fma_f32 v[76:77], v[208:209], v[16:17], v[76:77]
	v_cvt_pk_bf16_f32 v48, v74, v75
	v_cvt_pk_bf16_f32 v49, v76, v77
	global_store_dwordx2 v45, v[48:49], s[68:69] offset:256
	v_lshlrev_b32_e32 v74, 16, v196
	v_and_b32_e32 v75, 0xffff0000, v196
	v_pk_mul_f32 v[210:211], v[210:211], s[8:9] op_sel_hi:[1,0]
	v_lshlrev_b32_e32 v76, 16, v197
	v_and_b32_e32 v77, 0xffff0000, v197
	v_pk_mul_f32 v[212:213], v[212:213], s[8:9] op_sel_hi:[1,0]
	v_pk_fma_f32 v[74:75], v[210:211], v[6:7], v[74:75]
	v_pk_fma_f32 v[76:77], v[212:213], v[8:9], v[76:77]
	v_cvt_pk_bf16_f32 v48, v74, v75
	v_cvt_pk_bf16_f32 v49, v76, v77
	global_store_dwordx2 v45, v[48:49], s[68:69] offset:288
